# sample RWKV chain runs at s_setprio 3 instead of 2
# baseline (speedup 1.0000x reference)
.LBB0_1250:
	s_or_b64 exec, exec, s[0:1]
	v_readlane_b32 s0, v206, 44
	v_readlane_b32 s1, v206, 45
	s_mov_b32 s2, s0
	v_writelane_b32 v206, s0, 44
	s_mov_b32 s3, s83
	v_lshlrev_b32_e32 v5, 4, v4
	v_writelane_b32 v206, s1, 45
	v_lshl_add_u64 v[2:3], v[2:3], 0, s[2:3]
	v_and_b32_e32 v106, 0xf0, v5
	v_bfe_u32 v51, v4, 3, 1
	v_readlane_b32 s0, v206, 14
	v_lshlrev_b32_e32 v4, 3, v4
	v_lshl_add_u64 v[92:93], v[2:3], 0, v[106:107]
	v_lshlrev_b32_e32 v2, 10, v51
	v_mov_b32_e32 v3, v107
	v_readlane_b32 s1, v206, 15
	v_and_b32_e32 v72, 56, v4
	v_lshlrev_b32_e32 v4, 1, v72
	v_lshl_add_u64 v[2:3], s[0:1], 0, v[2:3]
	v_mov_b32_e32 v5, v107
	v_lshl_add_u64 v[94:95], v[2:3], 0, v[4:5]
	v_ashrrev_i32_e32 v47, 31, v46
	s_setprio 3
	v_xad_u32 v2, v1, -1, s18
	s_waitcnt vmcnt(2)
	v_sub_u32_e32 v32, s18, v1
	v_cndmask_b32_e64 v2, v2, v1, s[16:17]
	v_readlane_b32 s2, v206, 6
	v_add_u32_e32 v4, 4, v1
	v_add_u32_e32 v5, -5, v32
	v_add_u32_e32 v2, s2, v2
	v_cndmask_b32_e64 v4, v5, v4, s[16:17]
	v_ashrrev_i32_e32 v3, 31, v2
	v_add_u32_e32 v4, s2, v4
	v_lshlrev_b64 v[2:3], 10, v[2:3]
	v_ashrrev_i32_e32 v5, 31, v4
	v_lshl_add_u64 v[2:3], v[92:93], 0, v[2:3]
	v_lshlrev_b64 v[4:5], 10, v[4:5]
	v_lshl_add_u64 v[4:5], v[92:93], 0, v[4:5]
	global_load_dwordx4 v[52:55], v[2:3], off
	global_load_dwordx4 v[56:59], v[4:5], off
	v_add_u32_e32 v2, 8, v1
	v_add_u32_e32 v3, -9, v32
	v_cndmask_b32_e64 v2, v3, v2, s[16:17]
	v_add_u32_e32 v4, 12, v1
	v_add_u32_e32 v5, -13, v32
	v_add_u32_e32 v2, s2, v2
	v_cndmask_b32_e64 v4, v5, v4, s[16:17]
	v_ashrrev_i32_e32 v3, 31, v2
	v_add_u32_e32 v4, s2, v4
	v_lshlrev_b64 v[2:3], 10, v[2:3]
	v_ashrrev_i32_e32 v5, 31, v4
	v_lshl_add_u64 v[2:3], v[92:93], 0, v[2:3]
	v_lshlrev_b64 v[4:5], 10, v[4:5]
	v_lshl_add_u64 v[4:5], v[92:93], 0, v[4:5]
	global_load_dwordx4 v[60:63], v[2:3], off
	global_load_dwordx4 v[64:67], v[4:5], off
	v_xad_u32 v2, v91, -1, s18
	v_cndmask_b32_e64 v2, v2, v91, s[16:17]
	v_add_u32_e32 v2, s2, v2
	v_mad_i64_i32 v[2:3], s[0:1], v2, s37, v[94:95]
	global_load_dwordx4 v[68:71], v[2:3], off
	v_add_u32_e32 v2, 16, v1
	v_subrev_u32_e32 v3, 17, v32
	v_add_u32_e32 v4, 20, v1
	v_subrev_u32_e32 v5, 21, v32
	v_add_u32_e32 v10, 24, v1
	v_subrev_u32_e32 v11, 25, v32
	v_add_u32_e32 v12, 28, v1
	v_subrev_u32_e32 v13, 29, v32
	v_cndmask_b32_e64 v2, v3, v2, s[16:17]
	v_cndmask_b32_e64 v4, v5, v4, s[16:17]
	v_cndmask_b32_e64 v10, v11, v10, s[16:17]
	v_cndmask_b32_e64 v12, v13, v12, s[16:17]
	s_waitcnt vmcnt(5)
	v_sub_u32_e32 v38, s18, v91
	v_add_u32_e32 v2, s2, v2
	v_add_u32_e32 v4, s2, v4
	v_add_u32_e32 v10, s2, v10
	v_add_u32_e32 v12, s2, v12
	v_subrev_u32_e32 v18, 17, v38
	v_add_u32_e32 v19, 16, v91
	v_ashrrev_i32_e32 v3, 31, v2
	v_ashrrev_i32_e32 v5, 31, v4
	v_ashrrev_i32_e32 v11, 31, v10
	v_ashrrev_i32_e32 v13, 31, v12
	v_cndmask_b32_e64 v18, v18, v19, s[16:17]
	v_lshlrev_b64 v[2:3], 10, v[2:3]
	v_lshlrev_b64 v[4:5], 10, v[4:5]
	v_lshlrev_b64 v[10:11], 10, v[10:11]
	v_lshlrev_b64 v[12:13], 10, v[12:13]
	v_add_u32_e32 v18, s2, v18
	v_lshl_add_u64 v[2:3], v[92:93], 0, v[2:3]
	v_lshl_add_u64 v[6:7], v[92:93], 0, v[4:5]
	v_lshl_add_u64 v[10:11], v[92:93], 0, v[10:11]
	v_lshl_add_u64 v[14:15], v[92:93], 0, v[12:13]
	v_mad_i64_i32 v[18:19], s[0:1], v18, s37, v[94:95]
	global_load_dwordx4 v[2:5], v[2:3], off
	s_nop 0
	global_load_dwordx4 v[6:9], v[6:7], off
	s_nop 0
	global_load_dwordx4 v[10:13], v[10:11], off
	s_nop 0
	global_load_dwordx4 v[14:17], v[14:15], off
	v_add_u32_e32 v20, 36, v1
	global_load_dwordx4 v[26:29], v[18:19], off
	v_add_u32_e32 v18, 32, v1
	v_subrev_u32_e32 v19, 33, v32
	v_subrev_u32_e32 v21, 37, v32
	v_add_u32_e32 v30, 40, v1
	v_subrev_u32_e32 v31, 41, v32
	v_add_u32_e32 v33, 44, v1
	v_subrev_u32_e32 v32, 45, v32
	v_cndmask_b32_e64 v18, v19, v18, s[16:17]
	v_cndmask_b32_e64 v20, v21, v20, s[16:17]
	v_cndmask_b32_e64 v30, v31, v30, s[16:17]
	v_cndmask_b32_e64 v32, v32, v33, s[16:17]
	v_add_u32_e32 v18, s2, v18
	v_add_u32_e32 v20, s2, v20
	v_add_u32_e32 v30, s2, v30
	v_add_u32_e32 v32, s2, v32
	v_subrev_u32_e32 v38, 33, v38
	v_add_u32_e32 v39, 32, v91
	v_ashrrev_i32_e32 v19, 31, v18
	v_ashrrev_i32_e32 v21, 31, v20
	v_ashrrev_i32_e32 v31, 31, v30
	v_ashrrev_i32_e32 v33, 31, v32
	v_cndmask_b32_e64 v38, v38, v39, s[16:17]
	v_lshlrev_b64 v[18:19], 10, v[18:19]
	v_lshlrev_b64 v[20:21], 10, v[20:21]
	v_lshlrev_b64 v[30:31], 10, v[30:31]
	v_lshlrev_b64 v[32:33], 10, v[32:33]
	v_add_u32_e32 v38, s2, v38
	v_lshl_add_u64 v[18:19], v[92:93], 0, v[18:19]
	v_lshl_add_u64 v[22:23], v[92:93], 0, v[20:21]
	v_lshl_add_u64 v[30:31], v[92:93], 0, v[30:31]
	v_lshl_add_u64 v[34:35], v[92:93], 0, v[32:33]
	v_mad_i64_i32 v[38:39], s[0:1], v38, s37, v[94:95]
	global_load_dwordx4 v[18:21], v[18:19], off
	s_nop 0
	global_load_dwordx4 v[22:25], v[22:23], off
	s_nop 0
	global_load_dwordx4 v[30:33], v[30:31], off
	s_nop 0
	global_load_dwordx4 v[34:37], v[34:35], off
	v_lshl_or_b32 v50, v50, 8, v106
	global_load_dwordx4 v[38:41], v[38:39], off
	s_movk_i32 s2, 0x600
	v_mad_u64_u32 v[96:97], s[0:1], v1, s2, v[50:51]
	v_readlane_b32 s0, v206, 24
	v_readlane_b32 s1, v206, 25
	v_lshlrev_b32_e32 v103, 2, v46
	v_mul_lo_u32 v50, v91, s2
	v_lshl_add_u64 v[98:99], v[46:47], 2, s[0:1]
	v_lshlrev_b32_e32 v46, 2, v48
	v_mad_u32_u24 v125, v87, s2, v153
	v_mad_u32_u24 v126, v87, s2, v154
	v_mad_u32_u24 v127, v87, s2, s2
	v_lshl_or_b32 v46, v1, 4, v46
	v_readlane_b32 s2, v206, 41
	s_waitcnt vmcnt(14)
	ds_write_b128 v96, v[52:55]
	s_waitcnt vmcnt(13)
	ds_write_b128 v96, v[56:59] offset:6144
	s_waitcnt vmcnt(12)
	ds_write_b128 v96, v[60:63] offset:12288
	s_waitcnt vmcnt(11)
	ds_write_b128 v96, v[64:67] offset:18432
	v_lshlrev_b32_e32 v51, 8, v51
	v_lshlrev_b32_e32 v52, 2, v72
	v_add_u32_e32 v128, s2, v46
	v_readlane_b32 s2, v206, 37
	v_or3_b32 v97, v50, v51, v52
	s_waitcnt vmcnt(10)
	v_lshlrev_b32_e32 v50, 16, v68
	v_and_b32_e32 v51, 0xffff0000, v68
	v_lshlrev_b32_e32 v52, 16, v69
	v_and_b32_e32 v53, 0xffff0000, v69
	v_lshlrev_b32_e32 v47, 2, v87
	v_add3_u32 v46, s2, v49, v48
	ds_write_b128 v97, v[50:53] offset:1024
	v_lshlrev_b32_e32 v50, 16, v70
	v_and_b32_e32 v51, 0xffff0000, v70
	v_lshlrev_b32_e32 v52, 16, v71
	v_and_b32_e32 v53, 0xffff0000, v71
	v_cmp_eq_u32_e64 s[0:1], 15, v87
	v_or_b32_e32 v105, 0x6000, v90
	v_or_b32_e32 v109, 0x6100, v90
	v_or_b32_e32 v110, 0x6200, v90
	v_or_b32_e32 v111, 0x6300, v90
	v_or_b32_e32 v112, 0x6400, v90
	v_or_b32_e32 v114, 0x6600, v90
	v_or_b32_e32 v115, 0x6700, v90
	v_or_b32_e32 v116, 0x6800, v90
	v_or_b32_e32 v117, 0x6900, v90
	v_or_b32_e32 v118, 0x6a00, v90
	v_or_b32_e32 v119, 0x6c00, v90
	v_or_b32_e32 v120, 0x6d00, v90
	v_or_b32_e32 v121, 0x6e00, v90
	v_or_b32_e32 v122, 0x6f00, v90
	v_or_b32_e32 v123, 0x7000, v90
	v_mul_u32_u24_e32 v124, 0x600, v87
	s_mov_b32 s7, 0
	v_sub_u32_e32 v129, 0, v87
	v_lshl_add_u32 v130, v46, 2, v155
	v_or_b32_e32 v131, 0x7200, v90
	v_lshlrev_b32_e32 v106, 2, v47
	v_readlane_b32 s3, v206, 7
	ds_write_b128 v97, v[50:53] offset:1040
	v_lshlrev_b32_e32 v102, 10, v1
	v_sub_u32_e32 v108, 0, v102
	v_cndmask_b32_e64 v254, v108, v102, s[16:17]
	v_ashrrev_i32_e32 v255, 31, v254
	v_lshl_add_u64 v[82:83], v[92:93], 0, v[254:255]
	v_add_u32_e32 v248, 0x1000, v102
	v_sub_u32_e32 v108, 0, v248
	v_cndmask_b32_e64 v254, v108, v248, s[16:17]
	v_ashrrev_i32_e32 v255, 31, v254
	v_lshl_add_u64 v[84:85], v[92:93], 0, v[254:255]
	v_add_u32_e32 v248, 0x2000, v102
	v_sub_u32_e32 v108, 0, v248
	v_cndmask_b32_e64 v254, v108, v248, s[16:17]
	v_ashrrev_i32_e32 v255, 31, v254
	v_lshl_add_u64 v[100:101], v[92:93], 0, v[254:255]
	v_add_u32_e32 v248, 0x3000, v102
	v_sub_u32_e32 v108, 0, v248
	v_cndmask_b32_e64 v254, v108, v248, s[16:17]
	v_ashrrev_i32_e32 v255, 31, v254
	v_lshl_add_u64 v[202:203], v[92:93], 0, v[254:255]
	v_mul_lo_u32 v248, v91, s37
	v_sub_u32_e32 v108, 0, v248
	v_cndmask_b32_e64 v254, v108, v248, s[16:17]
	v_ashrrev_i32_e32 v255, 31, v254
	v_lshl_add_u64 v[252:253], v[94:95], 0, v[254:255]
	s_waitcnt lgkmcnt(0)
	s_barrier
